# kernel start: grid-sync arrival and wait moved to wave 1, S5 item's LDS ticket hand-off dropped (item = workgroup id)
# speedup vs baseline: 1.0059x; 1.0015x over previous
.LBB0_14:
	v_lshrrev_b32_e32 v1, 20, v0
	v_lshrrev_b32_e32 v0, 10, v0
	v_or_b32_e32 v0, v0, v1
	s_movk_i32 s6, 0x3ff
	v_and_or_b32 v0, v0, s6, v208
	v_cmp_eq_u32_e32 vcc, 64, v0
	s_waitcnt lgkmcnt(0)
	s_barrier
	s_and_saveexec_b64 s[6:7], vcc
	s_cbranch_execz .Lgs_arrived
	s_cmp_lg_u32 s2, 0
	s_cbranch_scc1 .Lgs_nowb
	buffer_wbl2 sc1

.Lssa_450:
	v_mov_b32_e32 v4, s2
	s_movk_i32 s4, 0xff
	s_waitcnt lgkmcnt(0)
	v_cmp_lt_i32_e32 vcc, s4, v4
	v_readfirstlane_b32 s83, v4
	s_mov_b64 s[4:5], -1
	s_cbranch_vccnz .Lssa_449
	s_ashr_i32 s82, s83, 2
	s_and_b32 s97, s83, 3
	s_and_saveexec_b64 s[84:85], s[6:7]
	s_cbranch_execz .Lssa_466
	s_ashr_i32 s83, s82, 31
	s_lshl_b64 s[4:5], s[82:83], 2
	s_add_u32 s4, s36, s4
	s_addc_u32 s5, s37, s5
	global_load_dword v90, v9, s[4:5]
	v_lshl_or_b32 v48, s82, 6, v208
	v_ashrrev_i32_e32 v49, 31, v48
	v_lshlrev_b64 v[4:5], 2, v[48:49]
	v_lshl_add_u64 v[6:7], s[10:11], 0, v[4:5]
	global_load_dword v50, v[6:7], off
	v_lshl_add_u64 v[4:5], s[8:9], 0, v[4:5]
	global_load_dword v8, v[4:5], off
	v_mov_b32_e32 v37, v23
	v_mov_b64_e32 v[84:85], v[36:37]
	s_mov_b32 s4, 0x44800000
	s_mov_b32 s5, 0xc4866000
	v_mov_b64_e32 v[6:7], v[30:31]
	v_mov_b64_e32 v[58:59], v[40:41]
	v_mov_b64_e32 v[52:53], v[32:33]
	v_mov_b64_e32 v[60:61], v[42:43]
	v_mov_b32_e32 v44, v34
	v_mov_b64_e32 v[54:55], v[34:35]
	v_mov_b64_e32 v[86:87], v[44:45]
	v_mov_b64_e32 v[62:63], v[46:47]
	v_mov_b64_e32 v[56:57], v[38:39]
	v_mov_b32_e32 v82, v38
	v_mov_b32_e32 v83, v25
	s_waitcnt vmcnt(2)
	v_cvt_f64_f32_e32 v[4:5], v90
	v_mul_f64 v[88:89], v[4:5], s[58:59]
	v_rndne_f64_e32 v[88:89], v[88:89]
	v_fmac_f64_e32 v[4:5], s[60:61], v[88:89]
	v_fmac_f64_e32 v[4:5], s[62:63], v[88:89]
	v_cvt_i32_f64_e32 v37, v[88:89]
	v_fma_f64 v[88:89], s[64:65], v[4:5], v[12:13]
	v_fma_f64 v[88:89], v[4:5], v[88:89], v[14:15]
	v_fma_f64 v[88:89], v[4:5], v[88:89], v[16:17]
	v_fma_f64 v[88:89], v[4:5], v[88:89], v[18:19]
	v_fma_f64 v[88:89], v[4:5], v[88:89], v[20:21]
	v_fma_f64 v[88:89], v[4:5], v[88:89], v[22:23]
	v_fma_f64 v[88:89], v[4:5], v[88:89], v[24:25]
	v_fma_f64 v[88:89], v[4:5], v[88:89], v[26:27]
	v_fma_f64 v[88:89], v[4:5], v[88:89], v[28:29]
	v_fma_f64 v[88:89], v[4:5], v[88:89], 1.0
	v_fma_f64 v[4:5], v[4:5], v[88:89], 1.0
	v_ldexp_f64 v[4:5], v[4:5], v37
	v_cmp_nlt_f32_e32 vcc, s4, v90
	v_cmp_ngt_f32_e64 s[4:5], s5, v90
	s_waitcnt vmcnt(1)
	v_cvt_f64_f32_e32 v[50:51], v50
	v_cndmask_b32_e32 v5, v80, v5, vcc
	s_and_b64 vcc, s[4:5], vcc
	v_cndmask_b32_e64 v5, 0, v5, s[4:5]
	v_cndmask_b32_e32 v4, 0, v4, vcc
	v_mul_f64 v[88:89], v[4:5], v[50:51]
	v_mul_f64 v[90:91], v[88:89], s[66:67]
	v_rndne_f64_e32 v[90:91], v[90:91]
	v_fmac_f64_e32 v[88:89], s[68:69], v[90:91]
	v_fmac_f64_e32 v[88:89], s[70:71], v[90:91]
	v_cvt_i32_f64_e32 v37, v[90:91]
	v_mul_f64 v[90:91], v[88:89], v[88:89]
	v_fmac_f64_e32 v[6:7], s[72:73], v[90:91]
	v_fmac_f64_e32 v[58:59], s[74:75], v[90:91]
	v_fmac_f64_e32 v[52:53], v[90:91], v[6:7]
	v_fmac_f64_e32 v[60:61], v[90:91], v[58:59]
	v_fmac_f64_e32 v[54:55], v[90:91], v[52:53]
	v_fmac_f64_e32 v[86:87], v[90:91], v[60:61]
	v_fmac_f64_e32 v[84:85], v[90:91], v[54:55]
	v_fmac_f64_e32 v[62:63], v[90:91], v[86:87]
	v_fmac_f64_e32 v[56:57], v[90:91], v[84:85]
	v_fmac_f64_e32 v[82:83], v[90:91], v[62:63]
	v_and_b32_e32 v37, 3, v37
	v_fma_f64 v[6:7], v[90:91], v[56:57], 1.0
	v_fma_f64 v[52:53], v[90:91], v[82:83], -0.5
	v_mul_f64 v[6:7], v[88:89], v[6:7]
	v_fma_f64 v[52:53], v[90:91], v[52:53], 1.0
	v_cmp_lt_i32_e32 vcc, 0, v37
	s_and_saveexec_b64 s[4:5], vcc
	s_cbranch_execz .Lssa_462
	v_cmp_ne_u32_e32 vcc, 1, v37
	v_xor_b32_e32 v55, 0x80000000, v7
	v_mov_b32_e32 v54, v6
	s_and_saveexec_b64 s[86:87], vcc
	s_xor_b64 s[86:87], exec, s[86:87]
	v_cmp_eq_u32_e32 vcc, 2, v37
	v_xor_b32_e32 v37, 0x80000000, v53
	s_nop 0
	v_cndmask_b32_e32 v56, v52, v6, vcc
	v_cndmask_b32_e64 v57, -v53, -v7, vcc
	v_cndmask_b32_e32 v55, v7, v37, vcc
	v_cndmask_b32_e32 v54, v6, v52, vcc
	v_mov_b64_e32 v[6:7], v[56:57]
	s_andn2_saveexec_b64 s[86:87], s[86:87]
	v_mov_b64_e32 v[6:7], v[52:53]
	s_or_b64 exec, exec, s[86:87]
	v_mov_b64_e32 v[52:53], v[54:55]

.Lssa_exit:
	v_readfirstlane_b32 s79, v208
	v_cmp_gt_u32_e64 s[4:5], 32, v208
	v_cmp_eq_u32_e32 vcc, 64, v208
	s_and_saveexec_b64 s[6:7], vcc
	s_cbranch_execz .LBB0_24
	s_load_dwordx2 s[8:9], s[0:1], 0x110
	v_mov_b32_e32 v0, 0
	v_mov_b32_e32 v1, s99
	s_waitcnt lgkmcnt(0)
	global_load_dword v2, v0, s[8:9] offset:32 sc1
	s_waitcnt vmcnt(0)
	v_and_b32_e32 v2, 0xffff0000, v2
	v_cmp_eq_u32_e32 vcc, v2, v1
	s_and_b64 exec, exec, vcc
	s_cbranch_execz .LBB0_23
	s_mov_b64 s[10:11], 0
